# prep: wg-weight f32->bf16 conversion loop unrolled 10x (all loads in flight before one wait) on top of v18 (merge stagger, norm1/norm2 block loops)
# speedup vs baseline: 1.0111x; 1.0043x over previous
.LBB0_28:
	v_lshl_add_u32 v2, s2, 9, v196
	s_mov_b32 s3, 0x140000
	v_cmp_gt_i32_e32 vcc, s3, v2
	s_lshl_b32 s28, s38, 9
	v_and_b32_e32 v1, 63, v196
	v_mov_b32_e32 v5, 0
	v_lshlrev_b32_e32 v8, 1, v196
	s_and_saveexec_b64 s[30:31], vcc
	s_cbranch_execz .LBB0_31
	s_waitcnt lgkmcnt(0)
	s_add_u32 s34, s6, 0xd00000
	s_addc_u32 s35, s7, 0
	v_and_b32_e32 v3, 15, v196
	v_and_b32_e32 v9, 0x60, v8
	s_mov_b64 s[36:37], 0
	v_mov_b32_e32 v10, s15
	v_mov_b32_e32 v11, s11
	v_mov_b32_e32 v12, s14
	v_mov_b32_e32 v13, s10
	v_lshlrev_b32_e32 v6, 2, v1
	v_mov_b32_e32 v7, v5
	s_mov_b32 s3, 0x13ffff
	v_mov_b32_e32 v14, v2
	s_cmp_lg_u32 s28, 0x20000
	s_cbranch_scc1 .LBB0_30
	v_bfe_u32 v22, v14, 15, 1
	v_ashrrev_i32_e32 v4, 18, v14
	v_bfe_u32 v17, v14, 14, 1
	v_mad_u32_u24 v20, v22, 5, v4
	v_cmp_eq_u32_e32 vcc, 0, v17
	v_ashrrev_i32_e32 v21, 31, v20
	v_bfe_u32 v15, v14, 6, 8
	v_ashrrev_i32_e32 v16, 16, v14
	v_cndmask_b32_e32 v19, v10, v11, vcc
	v_cndmask_b32_e32 v18, v12, v13, vcc
	v_lshlrev_b64 v[20:21], 18, v[20:21]
	v_lshlrev_b32_e32 v4, 10, v15
	v_lshlrev_b32_e32 v23, 8, v16
	v_lshl_add_u64 v[18:19], v[18:19], 0, v[20:21]
	v_lshl_add_u64 v[18:19], v[18:19], 0, v[4:5]
	v_and_b32_e32 v4, 0x300, v23
	v_lshl_add_u64 v[18:19], v[18:19], 0, v[4:5]
	v_lshl_add_u64 v[50:51], v[18:19], 0, v[6:7]
	s_mov_b32 s100, 0x40000
	s_mov_b32 s101, 0
	v_lshl_add_u64 v[52:53], v[50:51], 0, s[100:101]
	v_lshl_add_u64 v[54:55], v[52:53], 0, s[100:101]
	v_lshl_add_u64 v[56:57], v[54:55], 0, s[100:101]
	v_lshl_add_u64 v[58:59], v[56:57], 0, s[100:101]
	flat_load_dword v60, v[50:51]
	flat_load_dword v61, v[50:51] offset:512
	flat_load_dword v62, v[52:53]
	flat_load_dword v63, v[52:53] offset:512
	flat_load_dword v64, v[54:55]
	flat_load_dword v65, v[54:55] offset:512
	flat_load_dword v66, v[56:57]
	flat_load_dword v67, v[56:57] offset:512
	flat_load_dword v68, v[58:59]
	flat_load_dword v69, v[58:59] offset:512
	v_lshl_or_b32 v4, v22, 7, v9
	v_lshlrev_b32_e32 v19, 4, v17
	v_ashrrev_i32_e32 v17, 31, v16
	v_or3_b32 v4, v4, v19, v3
	v_lshlrev_b64 v[16:17], 17, v[16:17]
	v_lshl_or_b32 v16, v4, 9, v16
	v_lshl_add_u64 v[16:17], s[34:35], 0, v[16:17]
	v_lshlrev_b32_e32 v4, 1, v15
	v_lshl_add_u64 v[70:71], v[16:17], 0, v[4:5]
	v_lshl_add_u64 v[72:73], v[70:71], 0, s[100:101]
	v_lshl_add_u64 v[74:75], v[72:73], 0, s[100:101]
	v_lshl_add_u64 v[76:77], v[74:75], 0, s[100:101]
	v_lshl_add_u64 v[78:79], v[76:77], 0, s[100:101]
	v_lshl_add_u64 v[80:81], v[78:79], 0, s[100:101]
	v_lshl_add_u64 v[82:83], v[80:81], 0, s[100:101]
	v_lshl_add_u64 v[84:85], v[82:83], 0, s[100:101]
	v_lshl_add_u64 v[86:87], v[84:85], 0, s[100:101]
	v_lshl_add_u64 v[88:89], v[86:87], 0, s[100:101]
	s_waitcnt vmcnt(0) lgkmcnt(0)
	v_cvt_pk_bf16_f32 v60, v60, v60
	v_cvt_pk_bf16_f32 v61, v61, v61
	v_cvt_pk_bf16_f32 v62, v62, v62
	v_cvt_pk_bf16_f32 v63, v63, v63
	v_cvt_pk_bf16_f32 v64, v64, v64
	v_cvt_pk_bf16_f32 v65, v65, v65
	v_cvt_pk_bf16_f32 v66, v66, v66
	v_cvt_pk_bf16_f32 v67, v67, v67
	v_cvt_pk_bf16_f32 v68, v68, v68
	v_cvt_pk_bf16_f32 v69, v69, v69
	flat_store_short v[70:71], v60
	flat_store_short v[72:73], v61
	flat_store_short v[74:75], v62
	flat_store_short v[76:77], v63
	flat_store_short v[78:79], v64
	flat_store_short v[80:81], v65
	flat_store_short v[82:83], v66
	flat_store_short v[84:85], v67
	flat_store_short v[86:87], v68
	flat_store_short v[88:89], v69
	s_branch .LBB0_31
